# loader Y reduction done in-lane: each lane reads the 16 partials of one (chunk, step, row) as 4 x b128 and sums them (15 instructions per interval instead of ~150)
# speedup vs baseline: 1.0253x; 1.0031x over previous
; #define LAS __attribute__((address_space(3)))
; #define GAS __attribute__((address_space(1)))
; __device__ __forceinline__ void p0_transpose_item(const GAS float* W, int K, int N, GAS bf16* WT, int mode, LAS float* scr, int item, int lane) {
;     const int nblk = N / 32, kb = item / nblk, nb = item % nblk, k0 = 64 * kb, n0 = 32 * nb;
;     int r0 = n0;
;     if (mode & 1) { r0 = (n0 < DFF) ? (n0 / 128) * 256 + (n0 % 128) : ((n0 - DFF) / 128) * 256 + 128 + ((n0 - DFF) % 128); }
; __device__ __forceinline__ void p0_prologue(ArgP A, LAS unsigned char* lds, int tid, int lane, int wave, int bid, int G) {
;     ...
;     constexpr int I_IN = 32 * 165, I_OUT = 32 * 64, I_GU = 32 * 352, I_DN = 88 * 64, I_GT = 32 * 64, I_PL = 4 * 64, I_L = I_IN + I_OUT + I_GU + I_DN + I_GT + I_PL;
;     for (int it = gw; it < 2 * I_L; it += NGW) {
;         const int layer = it / I_L; int r = it - layer * I_L;
;         GAS unsigned char* wb = A->ws + (size_t)layer * WL_BYTES;
;         if (r < I_IN) { p0_transpose_item(A->in[12] + (size_t)layer * DM * 5280, DM, 5280, (GAS bf16*)(wb + WO_IN), 0 | (layer ? 2 : 0), scr, r, lane); continue; } r -= I_IN;
;         if (r < I_OUT) { p0_transpose_item(A->in[33] + (size_t)layer * DM * DM, DM, DM, (GAS bf16*)(wb + WO_OUT), 0 | (layer ? 2 : 0), scr, r, lane); continue; } r -= I_OUT;
;         if (r < I_GU) { p0_transpose_item(A->in[34] + (size_t)layer * DM * 2 * DFF, DM, 2 * DFF, (GAS bf16*)(wb + WO_GU), 1 | (layer ? 2 : 0), scr, r, lane); continue; } r -= I_GU;
;         if (r < I_DN) { p0_transpose_item(A->in[35] + (size_t)layer * DFF * DM, DFF, DM, (GAS bf16*)(wb + WO_DN), 0 | (layer ? 2 : 0), scr, r, lane); continue; } r -= I_DN;
;         if (r < I_GT) { p0_transpose_item(A->in[36] + (size_t)layer * DM * DM, DM, DM, (GAS bf16*)(wb + WO_GT), 0 | (layer ? 2 : 0), scr, r, lane); continue; } r -= I_GT;
;         p0_transpose_item(A->in[37] + (size_t)layer * PLED * DM, PLED, DM, (GAS bf16*)(wb + WO_PL), 0 | (layer ? 2 : 0), scr, r, lane);
.Lxp_cnt:
	s_waitcnt lgkmcnt(0)
	v_add_u32_e32 v1, 0, v22
	v_lshl_add_u32 v1, v1, 9, s2
	v_and_b32_e32 v2, 1, v1
	v_lshrrev_b32_e32 v1, 1, v1
	s_movk_i32 s24, 0x67a0
	v_cmp_le_u32_e32 vcc, s24, v1
	v_cndmask_b32_e64 v3, 0, 1, vcc
	v_mul_u32_u24_e32 v4, 0x67a0, v3
	v_sub_u32_e32 v4, v1, v4
	v_mov_b32_e32 v5, 0
	v_mov_b32_e32 v100, 0x14a0
	v_mov_b32_e32 v101, 0x800
	v_mov_b32_e32 v6, 0x2940000
	v_mov_b32_e32 v7, 0x0
	v_mov_b32_e32 v96, s28
	v_mov_b32_e32 v97, s29
	s_movk_i32 s24, 0x14a0
	v_cmp_le_u32_e32 vcc, s24, v4
	v_mov_b32_e32 v31, 0x14a0
	v_cndmask_b32_e32 v5, v5, v31, vcc
	v_mov_b32_e32 v31, 0x800
	v_cndmask_b32_e32 v100, v100, v31, vcc
	v_mov_b32_e32 v31, 0x800
	v_cndmask_b32_e32 v101, v101, v31, vcc
	v_mov_b32_e32 v31, 0x1000000
	v_cndmask_b32_e32 v6, v6, v31, vcc
	v_mov_b32_e32 v31, 0x1500000
	v_cndmask_b32_e32 v7, v7, v31, vcc
	v_mov_b32_e32 v31, s30
	v_cndmask_b32_e32 v96, v96, v31, vcc
	v_mov_b32_e32 v31, s31
	v_cndmask_b32_e32 v97, v97, v31, vcc
	s_movk_i32 s24, 0x1ca0
	v_cmp_le_u32_e32 vcc, s24, v4
	v_mov_b32_e32 v31, 0x1ca0
	v_cndmask_b32_e32 v5, v5, v31, vcc
	v_mov_b32_e32 v31, 0x2c00
	v_cndmask_b32_e32 v100, v100, v31, vcc
	v_mov_b32_e32 v31, 0x800
	v_cndmask_b32_e32 v101, v101, v31, vcc
	v_mov_b32_e32 v31, 0x5800000
	v_cndmask_b32_e32 v6, v6, v31, vcc
	v_mov_b32_e32 v31, 0x1d00000
	v_cndmask_b32_e32 v7, v7, v31, vcc
	v_mov_b32_e32 v31, s32
	v_cndmask_b32_e32 v96, v96, v31, vcc
	v_mov_b32_e32 v31, s33
	v_cndmask_b32_e32 v97, v97, v31, vcc
	s_movk_i32 s24, 0x48a0
	v_cmp_le_u32_e32 vcc, s24, v4
	v_mov_b32_e32 v31, 0x48a0
	v_cndmask_b32_e32 v5, v5, v31, vcc
	v_mov_b32_e32 v31, 0x800
	v_cndmask_b32_e32 v100, v100, v31, vcc
	v_mov_b32_e32 v31, 0x1600
	v_cndmask_b32_e32 v101, v101, v31, vcc
	v_mov_b32_e32 v31, 0x2c00000
	v_cndmask_b32_e32 v6, v6, v31, vcc
	v_mov_b32_e32 v31, 0x4900000
	v_cndmask_b32_e32 v7, v7, v31, vcc
	v_mov_b32_e32 v31, s44
	v_cndmask_b32_e32 v96, v96, v31, vcc
	v_mov_b32_e32 v31, s45
	v_cndmask_b32_e32 v97, v97, v31, vcc
	s_movk_i32 s24, 0x5ea0
	v_cmp_le_u32_e32 vcc, s24, v4
	v_mov_b32_e32 v31, 0x5ea0
	v_cndmask_b32_e32 v5, v5, v31, vcc
	v_mov_b32_e32 v31, 0x800
	v_cndmask_b32_e32 v100, v100, v31, vcc
	v_mov_b32_e32 v31, 0x800
	v_cndmask_b32_e32 v101, v101, v31, vcc
	v_mov_b32_e32 v31, 0x1000000
	v_cndmask_b32_e32 v6, v6, v31, vcc
	v_mov_b32_e32 v31, 0x5f00000
	v_cndmask_b32_e32 v7, v7, v31, vcc
	v_mov_b32_e32 v31, s62
	v_cndmask_b32_e32 v96, v96, v31, vcc
	v_mov_b32_e32 v31, s63
	v_cndmask_b32_e32 v97, v97, v31, vcc
	s_movk_i32 s24, 0x66a0
	v_cmp_le_u32_e32 vcc, s24, v4
	v_mov_b32_e32 v31, 0x66a0
	v_cndmask_b32_e32 v5, v5, v31, vcc
	v_mov_b32_e32 v31, 0x800
	v_cndmask_b32_e32 v100, v100, v31, vcc
	v_mov_b32_e32 v31, 0x100
	v_cndmask_b32_e32 v101, v101, v31, vcc
	v_mov_b32_e32 v31, 0x200000
	v_cndmask_b32_e32 v6, v6, v31, vcc
	v_mov_b32_e32 v31, 0x6700000
	v_cndmask_b32_e32 v7, v7, v31, vcc
	v_mov_b32_e32 v31, s18
	v_cndmask_b32_e32 v96, v96, v31, vcc
	v_mov_b32_e32 v31, s19
	v_cndmask_b32_e32 v97, v97, v31, vcc
	v_sub_u32_e32 v4, v4, v5
	v_lshrrev_b32_e32 v5, 6, v4
	v_mov_b32_e32 v8, 64
	s_movk_i32 s24, 0x14a0
	v_cmp_eq_u32_e32 vcc, s24, v100
	v_mul_u32_u24_e32 v31, 0x635, v4
	v_lshrrev_b32_e32 v31, 18, v31
	v_cndmask_b32_e32 v5, v5, v31, vcc
	v_mov_b32_e32 v31, 0xa5
	v_cndmask_b32_e32 v8, v8, v31, vcc
	s_movk_i32 s24, 0x2c00
	v_cmp_eq_u32_e32 vcc, s24, v100
	v_mul_u32_u24_e32 v31, 0xba3, v4
	v_lshrrev_b32_e32 v31, 20, v31
	v_cndmask_b32_e32 v5, v5, v31, vcc
	v_mov_b32_e32 v31, 0x160
	v_cndmask_b32_e32 v8, v8, v31, vcc
	v_mul_u32_u24_e32 v8, v5, v8
	v_sub_u32_e32 v4, v4, v8
	v_lshlrev_b32_e32 v4, 5, v4
	s_movk_i32 s24, 0x1600
	v_cmp_le_u32_e64 s[8:9], s24, v4
	v_subrev_u32_e32 v8, s24, v4
	v_cndmask_b32_e64 v8, v4, v8, s[8:9]
	v_cndmask_b32_e64 v31, 0, 1, s[8:9]
	v_lshlrev_b32_e32 v31, 7, v31
	v_and_b32_e32 v1, 0x7f, v8
	v_lshrrev_b32_e32 v8, 7, v8
	v_lshl_add_u32 v8, v8, 8, v1
	v_add_u32_e32 v8, v8, v31
	v_cndmask_b32_e32 v8, v4, v8, vcc
	v_lshlrev_b32_e32 v1, 5, v2
	v_lshl_add_u32 v1, v5, 6, v1
	v_mul_lo_u32 v1, v1, v100
	v_add_u32_e32 v1, v1, v4
	v_lshlrev_b32_e32 v1, 2, v1
	v_mul_lo_u32 v6, v6, v3
	v_add_u32_e32 v1, v1, v6
	v_add_co_u32_e32 v96, vcc, v96, v1
	v_addc_co_u32_e32 v97, vcc, 0, v97, vcc
	v_lshlrev_b32_e32 v101, 1, v101
	v_mul_lo_u32 v8, v8, v101
	v_add_u32_e32 v8, v8, v7
	v_lshl_add_u32 v8, v5, 7, v8
	v_lshl_add_u32 v8, v2, 6, v8
	s_mov_b32 s24, 0x6800000
	v_mul_lo_u32 v1, v3, s24
	v_add_u32_e32 v8, v8, v1
	v_mov_b32_e32 v1, s7
	v_add_co_u32_e32 v98, vcc, s6, v8
	v_addc_co_u32_e32 v99, vcc, 0, v1, vcc
	v_add_u32_e32 v1, 64, v22
	v_lshl_add_u32 v1, v1, 9, s2
	v_and_b32_e32 v2, 1, v1
	v_lshrrev_b32_e32 v1, 1, v1
	s_movk_i32 s24, 0x67a0
	v_cmp_le_u32_e32 vcc, s24, v1
	v_cndmask_b32_e64 v3, 0, 1, vcc
; #define LAS __attribute__((address_space(3)))
; #define GAS __attribute__((address_space(1)))
; __device__ __forceinline__ void p0_transpose_item(const GAS float* W, int K, int N, GAS bf16* WT, int mode, LAS float* scr, int item, int lane) {
;     const int nblk = N / 32, kb = item / nblk, nb = item % nblk, k0 = 64 * kb, n0 = 32 * nb;
;     int r0 = n0;
;     if (mode & 1) { r0 = (n0 < DFF) ? (n0 / 128) * 256 + (n0 % 128) : ((n0 - DFF) / 128) * 256 + 128 + ((n0 - DFF) % 128); }
; __device__ __forceinline__ void p0_prologue(ArgP A, LAS unsigned char* lds, int tid, int lane, int wave, int bid, int G) {
;     ...
;     constexpr int I_IN = 32 * 165, I_OUT = 32 * 64, I_GU = 32 * 352, I_DN = 88 * 64, I_GT = 32 * 64, I_PL = 4 * 64, I_L = I_IN + I_OUT + I_GU + I_DN + I_GT + I_PL;
;     for (int it = gw; it < 2 * I_L; it += NGW) {
;         const int layer = it / I_L; int r = it - layer * I_L;
;         GAS unsigned char* wb = A->ws + (size_t)layer * WL_BYTES;
;         if (r < I_IN) { p0_transpose_item(A->in[12] + (size_t)layer * DM * 5280, DM, 5280, (GAS bf16*)(wb + WO_IN), 0 | (layer ? 2 : 0), scr, r, lane); continue; } r -= I_IN;
;         if (r < I_OUT) { p0_transpose_item(A->in[33] + (size_t)layer * DM * DM, DM, DM, (GAS bf16*)(wb + WO_OUT), 0 | (layer ? 2 : 0), scr, r, lane); continue; } r -= I_OUT;
;         if (r < I_GU) { p0_transpose_item(A->in[34] + (size_t)layer * DM * 2 * DFF, DM, 2 * DFF, (GAS bf16*)(wb + WO_GU), 1 | (layer ? 2 : 0), scr, r, lane); continue; } r -= I_GU;
;         if (r < I_DN) { p0_transpose_item(A->in[35] + (size_t)layer * DFF * DM, DFF, DM, (GAS bf16*)(wb + WO_DN), 0 | (layer ? 2 : 0), scr, r, lane); continue; } r -= I_DN;
;         if (r < I_GT) { p0_transpose_item(A->in[36] + (size_t)layer * DM * DM, DM, DM, (GAS bf16*)(wb + WO_GT), 0 | (layer ? 2 : 0), scr, r, lane); continue; } r -= I_GT;
;         p0_transpose_item(A->in[37] + (size_t)layer * PLED * DM, PLED, DM, (GAS bf16*)(wb + WO_PL), 0 | (layer ? 2 : 0), scr, r, lane);
	v_mul_u32_u24_e32 v4, 0x67a0, v3
	v_sub_u32_e32 v4, v1, v4
	v_mov_b32_e32 v5, 0
	v_mov_b32_e32 v106, 0x14a0
	v_mov_b32_e32 v107, 0x800
	v_mov_b32_e32 v6, 0x2940000
	v_mov_b32_e32 v7, 0x0
	v_mov_b32_e32 v102, s28
	v_mov_b32_e32 v103, s29
	s_movk_i32 s24, 0x14a0
	v_cmp_le_u32_e32 vcc, s24, v4
	v_mov_b32_e32 v31, 0x14a0
	v_cndmask_b32_e32 v5, v5, v31, vcc
	v_mov_b32_e32 v31, 0x800
	v_cndmask_b32_e32 v106, v106, v31, vcc
	v_mov_b32_e32 v31, 0x800
	v_cndmask_b32_e32 v107, v107, v31, vcc
	v_mov_b32_e32 v31, 0x1000000
	v_cndmask_b32_e32 v6, v6, v31, vcc
	v_mov_b32_e32 v31, 0x1500000
	v_cndmask_b32_e32 v7, v7, v31, vcc
	v_mov_b32_e32 v31, s30
	v_cndmask_b32_e32 v102, v102, v31, vcc
	v_mov_b32_e32 v31, s31
	v_cndmask_b32_e32 v103, v103, v31, vcc
	s_movk_i32 s24, 0x1ca0
	v_cmp_le_u32_e32 vcc, s24, v4
	v_mov_b32_e32 v31, 0x1ca0
	v_cndmask_b32_e32 v5, v5, v31, vcc
	v_mov_b32_e32 v31, 0x2c00
	v_cndmask_b32_e32 v106, v106, v31, vcc
	v_mov_b32_e32 v31, 0x800
	v_cndmask_b32_e32 v107, v107, v31, vcc
	v_mov_b32_e32 v31, 0x5800000
	v_cndmask_b32_e32 v6, v6, v31, vcc
	v_mov_b32_e32 v31, 0x1d00000
	v_cndmask_b32_e32 v7, v7, v31, vcc
	v_mov_b32_e32 v31, s32
	v_cndmask_b32_e32 v102, v102, v31, vcc
	v_mov_b32_e32 v31, s33
	v_cndmask_b32_e32 v103, v103, v31, vcc
	s_movk_i32 s24, 0x48a0
	v_cmp_le_u32_e32 vcc, s24, v4
	v_mov_b32_e32 v31, 0x48a0
	v_cndmask_b32_e32 v5, v5, v31, vcc
	v_mov_b32_e32 v31, 0x800
	v_cndmask_b32_e32 v106, v106, v31, vcc
	v_mov_b32_e32 v31, 0x1600
	v_cndmask_b32_e32 v107, v107, v31, vcc
	v_mov_b32_e32 v31, 0x2c00000
	v_cndmask_b32_e32 v6, v6, v31, vcc
	v_mov_b32_e32 v31, 0x4900000
	v_cndmask_b32_e32 v7, v7, v31, vcc
	v_mov_b32_e32 v31, s44
	v_cndmask_b32_e32 v102, v102, v31, vcc
	v_mov_b32_e32 v31, s45
	v_cndmask_b32_e32 v103, v103, v31, vcc
	s_movk_i32 s24, 0x5ea0
	v_cmp_le_u32_e32 vcc, s24, v4
	v_mov_b32_e32 v31, 0x5ea0
	v_cndmask_b32_e32 v5, v5, v31, vcc
	v_mov_b32_e32 v31, 0x800
	v_cndmask_b32_e32 v106, v106, v31, vcc
	v_mov_b32_e32 v31, 0x800
	v_cndmask_b32_e32 v107, v107, v31, vcc
	v_mov_b32_e32 v31, 0x1000000
	v_cndmask_b32_e32 v6, v6, v31, vcc
	v_mov_b32_e32 v31, 0x5f00000
	v_cndmask_b32_e32 v7, v7, v31, vcc
	v_mov_b32_e32 v31, s62
	v_cndmask_b32_e32 v102, v102, v31, vcc
	v_mov_b32_e32 v31, s63
	v_cndmask_b32_e32 v103, v103, v31, vcc
	s_movk_i32 s24, 0x66a0
	v_cmp_le_u32_e32 vcc, s24, v4
	v_mov_b32_e32 v31, 0x66a0
	v_cndmask_b32_e32 v5, v5, v31, vcc
	v_mov_b32_e32 v31, 0x800
	v_cndmask_b32_e32 v106, v106, v31, vcc
	v_mov_b32_e32 v31, 0x100
	v_cndmask_b32_e32 v107, v107, v31, vcc
	v_mov_b32_e32 v31, 0x200000
	v_cndmask_b32_e32 v6, v6, v31, vcc
	v_mov_b32_e32 v31, 0x6700000
	v_cndmask_b32_e32 v7, v7, v31, vcc
	v_mov_b32_e32 v31, s18
	v_cndmask_b32_e32 v102, v102, v31, vcc
	v_mov_b32_e32 v31, s19
	v_cndmask_b32_e32 v103, v103, v31, vcc
	v_sub_u32_e32 v4, v4, v5
	v_lshrrev_b32_e32 v5, 6, v4
	v_mov_b32_e32 v8, 64
	s_movk_i32 s24, 0x14a0
	v_cmp_eq_u32_e32 vcc, s24, v106
	v_mul_u32_u24_e32 v31, 0x635, v4
	v_lshrrev_b32_e32 v31, 18, v31
	v_cndmask_b32_e32 v5, v5, v31, vcc
	v_mov_b32_e32 v31, 0xa5
	v_cndmask_b32_e32 v8, v8, v31, vcc
	s_movk_i32 s24, 0x2c00
	v_cmp_eq_u32_e32 vcc, s24, v106
	v_mul_u32_u24_e32 v31, 0xba3, v4
	v_lshrrev_b32_e32 v31, 20, v31
	v_cndmask_b32_e32 v5, v5, v31, vcc
	v_mov_b32_e32 v31, 0x160
	v_cndmask_b32_e32 v8, v8, v31, vcc
	v_mul_u32_u24_e32 v8, v5, v8
	v_sub_u32_e32 v4, v4, v8
	v_lshlrev_b32_e32 v4, 5, v4
	s_movk_i32 s24, 0x1600
	v_cmp_le_u32_e64 s[8:9], s24, v4
	v_subrev_u32_e32 v8, s24, v4
	v_cndmask_b32_e64 v8, v4, v8, s[8:9]
	v_cndmask_b32_e64 v31, 0, 1, s[8:9]
	v_lshlrev_b32_e32 v31, 7, v31
	v_and_b32_e32 v1, 0x7f, v8
	v_lshrrev_b32_e32 v8, 7, v8
	v_lshl_add_u32 v8, v8, 8, v1
	v_add_u32_e32 v8, v8, v31
	v_cndmask_b32_e32 v8, v4, v8, vcc
	v_lshlrev_b32_e32 v1, 5, v2
	v_lshl_add_u32 v1, v5, 6, v1
	v_mul_lo_u32 v1, v1, v106
	v_add_u32_e32 v1, v1, v4
	v_lshlrev_b32_e32 v1, 2, v1
	v_mul_lo_u32 v6, v6, v3
	v_add_u32_e32 v1, v1, v6
	v_add_co_u32_e32 v102, vcc, v102, v1
	v_addc_co_u32_e32 v103, vcc, 0, v103, vcc
	v_lshlrev_b32_e32 v107, 1, v107
	v_mul_lo_u32 v8, v8, v107
	v_add_u32_e32 v8, v8, v7
	v_lshl_add_u32 v8, v5, 7, v8
	v_lshl_add_u32 v8, v2, 6, v8
	s_mov_b32 s24, 0x6800000
	v_mul_lo_u32 v1, v3, s24
	v_add_u32_e32 v8, v8, v1
	v_mov_b32_e32 v1, s7
	v_add_co_u32_e32 v104, vcc, s6, v8
	v_addc_co_u32_e32 v105, vcc, 0, v1, vcc
	v_lshrrev_b32_e32 v1, 2, v22
	v_and_b32_e32 v1, 3, v1
	v_and_b32_e32 v2, 3, v22
	v_lshrrev_b32_e32 v3, 4, v22
	v_lshlrev_b32_e32 v26, 8, v1
	v_lshl_add_u32 v26, v2, 6, v26
	v_lshl_add_u32 v26, v3, 10, v26
	v_add_u32_e32 v26, s25, v26
	v_lshlrev_b32_e32 v27, 11, v1
	v_lshl_add_u32 v27, v2, 2, v27
	v_lshl_add_u32 v27, v3, 13, v27
	s_mov_b32 s23, 0
	s_mov_b32 s22, 0
	s_mov_b32 s14, 0
	s_mov_b32 s17, 0
	s_mov_b32 s18, 0

; #define LAS __attribute__((address_space(3)))
; #define R4_ISSUE(cc, slot) do { const GAS float* g_ = gp + (size_t)(cc) * 2048; LAS float* l_ = ring + (slot) * 1536; _Pragma("unroll") for (int i_ = 0; i_ < 6; ++i_) \
;         __builtin_amdgcn_global_load_lds((const GAS unsigned*)(g_ + off[i_]), (LAS unsigned*)(l_ + i_ * 256), 16, 0, 0); } while (0)
; #define R4_LOAD(o, sb_) do { const LAS float* sb = (sb_); (o).r = *(const LAS f32x4*)(sb + cgp * 4); (o).w = *(const LAS f32x4*)(sb + 64 + cgp * 4); (o).k = *(const LAS f32x4*)(sb + 128 + cgp * 4); \
;         (o).a = *(const LAS f32x4*)(sb + 256 + cgp * 4); (o).b = *(const LAS f32x4*)(sb + 320 + cgp * 4); (o).vv = sb[192 + rq * 4 + rl]; asm volatile("" ::: "memory"); } while (0)
; __device__ __forceinline__ void rwkv_prompt_wave4(LAS float* ring, const GAS float* RW, int mbase, int h, int rq, GAS float* Sout, GAS float* YR, int lane) {
;     ...
;     for (int ci = 0; ci < NCH; ++ci) {
;         { const int cn = ci + 3; const int cl = cn < NCH ? cn : NCH - 1; R4_ISSUE(cl, cn % R4_NS); }
;         const LAS float* cb = ring + (ci % R4_NS) * 1536; const LAS float* nb = ring + ((ci + 1) % R4_NS) * 1536;
;         R4_LOAD(oC, cb + 768);  R4_STEP(oA, 0);
;         R4_LOAD(oD, cb + 1152); R4_STEP(oB, 1);
;         asm volatile("s_waitcnt vmcnt(12)" ::: "memory");
.Lld_loop:
	s_cmp_eq_u32 s18, 0x80
	s_cbranch_scc1 .Lld_bar
	s_cmp_ge_u32 s1, 2
	s_cbranch_scc1 .Lld_w1
	s_cmp_eq_u32 s18, 0
	s_cbranch_scc1 .Lld_w0a
	s_cmp_eq_u32 s18, 1
	s_cbranch_scc1 .Lld_w0b
	s_cmp_eq_u32 s18, 2
	s_cbranch_scc1 .Lld_w0c
	s_waitcnt vmcnt(24)
	s_branch .Lld_bar

; #define LAS __attribute__((address_space(3)))
; #define R4_ISSUE(cc, slot) do { const GAS float* g_ = gp + (size_t)(cc) * 2048; LAS float* l_ = ring + (slot) * 1536; _Pragma("unroll") for (int i_ = 0; i_ < 6; ++i_) \
;         __builtin_amdgcn_global_load_lds((const GAS unsigned*)(g_ + off[i_]), (LAS unsigned*)(l_ + i_ * 256), 16, 0, 0); } while (0)
; #define R4_LOAD(o, sb_) do { const LAS float* sb = (sb_); (o).r = *(const LAS f32x4*)(sb + cgp * 4); (o).w = *(const LAS f32x4*)(sb + 64 + cgp * 4); (o).k = *(const LAS f32x4*)(sb + 128 + cgp * 4); \
;         (o).a = *(const LAS f32x4*)(sb + 256 + cgp * 4); (o).b = *(const LAS f32x4*)(sb + 320 + cgp * 4); (o).vv = sb[192 + rq * 4 + rl]; asm volatile("" ::: "memory"); } while (0)
; __device__ __forceinline__ void rwkv_prompt_wave4(LAS float* ring, const GAS float* RW, int mbase, int h, int rq, GAS float* Sout, GAS float* YR, int lane) {
;     ...
;     for (int ci = 0; ci < NCH; ++ci) {
;         { const int cn = ci + 3; const int cl = cn < NCH ? cn : NCH - 1; R4_ISSUE(cl, cn % R4_NS); }
;         const LAS float* cb = ring + (ci % R4_NS) * 1536; const LAS float* nb = ring + ((ci + 1) % R4_NS) * 1536;
;         R4_LOAD(oC, cb + 768);  R4_STEP(oA, 0);
;         R4_LOAD(oD, cb + 1152); R4_STEP(oB, 1);
;         asm volatile("s_waitcnt vmcnt(12)" ::: "memory");
.Lld_w0c:
	s_waitcnt vmcnt(23)
	s_branch .Lld_bar
.Lld_w1:
	s_cmp_eq_u32 s18, 0
	s_cbranch_scc1 .Lld_w1a
	s_cmp_eq_u32 s18, 1
	s_cbranch_scc1 .Lld_w1b
	s_cmp_eq_u32 s18, 2
	s_cbranch_scc1 .Lld_w1c
	s_waitcnt vmcnt(17)
	s_branch .Lld_bar

; #define LAS __attribute__((address_space(3)))
; #define R4_ISSUE(cc, slot) do { const GAS float* g_ = gp + (size_t)(cc) * 2048; LAS float* l_ = ring + (slot) * 1536; _Pragma("unroll") for (int i_ = 0; i_ < 6; ++i_) \
;         __builtin_amdgcn_global_load_lds((const GAS unsigned*)(g_ + off[i_]), (LAS unsigned*)(l_ + i_ * 256), 16, 0, 0); } while (0)
; #define R4_LOAD(o, sb_) do { const LAS float* sb = (sb_); (o).r = *(const LAS f32x4*)(sb + cgp * 4); (o).w = *(const LAS f32x4*)(sb + 64 + cgp * 4); (o).k = *(const LAS f32x4*)(sb + 128 + cgp * 4); \
;         (o).a = *(const LAS f32x4*)(sb + 256 + cgp * 4); (o).b = *(const LAS f32x4*)(sb + 320 + cgp * 4); (o).vv = sb[192 + rq * 4 + rl]; asm volatile("" ::: "memory"); } while (0)
; __device__ __forceinline__ void rwkv_prompt_wave4(LAS float* ring, const GAS float* RW, int mbase, int h, int rq, GAS float* Sout, GAS float* YR, int lane) {
;     ...
;     for (int ci = 0; ci < NCH; ++ci) {
;         { const int cn = ci + 3; const int cl = cn < NCH ? cn : NCH - 1; R4_ISSUE(cl, cn % R4_NS); }
;         const LAS float* cb = ring + (ci % R4_NS) * 1536; const LAS float* nb = ring + ((ci + 1) % R4_NS) * 1536;
;         R4_LOAD(oC, cb + 768);  R4_STEP(oA, 0);
;         R4_LOAD(oD, cb + 1152); R4_STEP(oB, 1);
;         asm volatile("s_waitcnt vmcnt(12)" ::: "memory");
.Lld_w1c:
	s_waitcnt vmcnt(16)

; __device__ __forceinline__ void rwkv_prompt_wave4(LAS float* ring, const GAS float* RW, int mbase, int h, int rq, GAS float* Sout, GAS float* YR, int lane) {
;     ...
;         if (cgp < 4) YR[(size_t)(mbase + ci * 4 + cgp) * 512 + h * 64 + rq * 4 + rl] = ykeep;
.Lld_y:
	v_add_u32_e32 v28, s22, v26
	ds_read_b128 v[32:35], v28
	ds_read_b128 v[36:39], v28 offset:16
	ds_read_b128 v[40:43], v28 offset:32
	ds_read_b128 v[44:47], v28 offset:48
	s_xor_b32 s22, s22, 0x1000
	s_waitcnt lgkmcnt(0)
	v_pk_add_f32 v[32:33], v[32:33], v[34:35]
	v_pk_add_f32 v[36:37], v[36:37], v[38:39]
	v_pk_add_f32 v[40:41], v[40:41], v[42:43]
	v_pk_add_f32 v[44:45], v[44:45], v[46:47]
	v_pk_add_f32 v[32:33], v[32:33], v[36:37]
	v_pk_add_f32 v[40:41], v[40:41], v[44:45]
	s_nop 0
	v_pk_add_f32 v[32:33], v[32:33], v[40:41]
	s_nop 0
	v_add_f32_e32 v32, v32, v33
	global_store_dword v27, v32, s[98:99]
	s_add_u32 s98, s98, 0x8000
	s_addc_u32 s99, s99, 0
